# LN row mapping XCD-aligned with GEMM ownership, quarters processed most-recently-written first (L2 hits on Y)
# speedup vs baseline: 1.0129x; 1.0129x over previous
.LBB0_323:
	s_or_b64 exec, exec, s[0:1]
	s_cmpk_lt_i32 s33, 0x2000
	s_waitcnt lgkmcnt(0)
	v_mov_b32_e32 v0, v180
	s_movk_i32 s57, 0x2000
	s_cselect_b64 s[30:31], -1, 0
	s_cmpk_gt_i32 s33, 0x1fff
	v_mbcnt_lo_u32_b32 v183, -1, 0
	s_barrier
	s_cbranch_scc1 .LBB0_326
	v_mbcnt_hi_u32_b32 v2, -1, v183
	v_and_b32_e32 v3, 64, v2
	v_add_u32_e32 v3, 64, v3
	v_xor_b32_e32 v4, 1, v2
	v_cmp_lt_i32_e32 vcc, v4, v3
	s_bfe_u32 s36, s33, 0x30003
	s_lshl_b32 s36, s36, 12
	s_lshr_b32 s44, s33, 6
	s_lshl_b32 s44, s44, 5
	s_add_i32 s36, s36, s44
	s_and_b32 s44, s33, 7
	s_lshl_b32 s44, s44, 2
	s_add_i32 s36, s36, s44
	s_addk_i32 s36, 0xc00
	s_ashr_i32 s37, s36, 31
	v_cndmask_b32_e32 v4, v2, v4, vcc
	v_lshlrev_b32_e32 v86, 2, v4
	v_xor_b32_e32 v4, 2, v2
	v_cmp_lt_i32_e32 vcc, v4, v3
	s_movk_i32 s44, 0xfc00
	s_lshl_b64 s[0:1], s[36:37], 9
	v_cndmask_b32_e32 v4, v2, v4, vcc
	v_lshlrev_b32_e32 v87, 2, v4
	v_xor_b32_e32 v4, 4, v2
	v_cmp_lt_i32_e32 vcc, v4, v3
	s_add_u32 s46, s40, s0
	s_addc_u32 s47, s41, s1
	v_cndmask_b32_e32 v4, v2, v4, vcc
	v_lshlrev_b32_e32 v88, 2, v4
	v_xor_b32_e32 v4, 8, v2
	v_cmp_lt_i32_e32 vcc, v4, v3
	s_ashr_i32 s45, s44, 31
	s_lshl_b64 s[48:49], s[44:45], 9
	v_cndmask_b32_e32 v4, v2, v4, vcc
	v_lshlrev_b32_e32 v89, 2, v4
	v_xor_b32_e32 v4, 16, v2
	v_cmp_lt_i32_e32 vcc, v4, v3
	s_lshl_b64 s[0:1], s[36:37], 11
	s_add_u32 s52, s40, s0
	v_cndmask_b32_e32 v4, v2, v4, vcc
	v_lshlrev_b32_e32 v90, 2, v4
	v_xor_b32_e32 v4, 32, v2
	v_cmp_lt_i32_e32 vcc, v4, v3
	s_addc_u32 s53, s41, s1
	s_lshl_b64 s[54:55], s[44:45], 11
	s_lshl_b64 s[0:1], s[36:37], 12
	v_ashrrev_i32_e32 v1, 31, v0
	v_cndmask_b32_e32 v2, v2, v4, vcc
	s_add_u32 s0, s16, s0
	v_lshlrev_b32_e32 v91, 2, v2
	v_lshlrev_b64 v[2:3], 4, v[0:1]
	s_addc_u32 s1, s17, s1
	v_lshl_add_u64 v[24:25], s[26:27], 0, v[2:3]
	v_lshl_add_u64 v[26:27], s[28:29], 0, v[2:3]
	v_lshlrev_b64 v[28:29], 3, v[0:1]
	v_lshl_add_u64 v[30:31], s[0:1], 0, v[2:3]
	s_lshl_b64 s[16:17], s[44:45], 12
	s_mov_b32 s56, 0x3fb504f3
	v_mov_b32_e32 v92, 0x3727c5ac
	s_mov_b32 s37, 0xf800000
	v_mov_b32_e32 v93, 0x260
	s_movk_i32 s45, 0x7fff
	s_mov_b32 s58, 0x7000000
	s_mov_b32 s59, 0x7001000
	s_mov_b32 s60, 0x1b400000
	s_movk_i32 s36, 0x7ffc
	s_mov_b32 s44, 1

.LBB0_660:
	s_or_b64 exec, exec, s[0:1]
	v_cndmask_b32_e64 v1, 0, 1, s[30:31]
	s_waitcnt lgkmcnt(0)
	v_mov_b32_e32 v0, v180
	v_cmp_ne_u32_e64 s[4:5], 1, v1
	s_andn2_b64 vcc, exec, s[30:31]
	s_barrier
	s_cbranch_vccnz .LBB0_663
	v_mbcnt_hi_u32_b32 v2, -1, v183
	v_and_b32_e32 v3, 64, v2
	v_add_u32_e32 v3, 64, v3
	v_xor_b32_e32 v4, 1, v2
	v_cmp_lt_i32_e32 vcc, v4, v3
	v_ashrrev_i32_e32 v1, 31, v0
	s_bfe_u32 s30, s33, 0x30003
	s_lshl_b32 s30, s30, 12
	s_lshr_b32 s36, s33, 6
	s_lshl_b32 s36, s36, 5
	s_add_i32 s30, s30, s36
	s_and_b32 s36, s33, 7
	s_lshl_b32 s36, s36, 2
	s_add_i32 s30, s30, s36
	s_addk_i32 s30, 0xc00
	v_cndmask_b32_e32 v4, v2, v4, vcc
	v_lshlrev_b32_e32 v98, 2, v4
	v_xor_b32_e32 v4, 2, v2
	v_cmp_lt_i32_e32 vcc, v4, v3
	s_mov_b64 s[0:1], 0x1000
	s_ashr_i32 s31, s30, 31
	v_cndmask_b32_e32 v4, v2, v4, vcc
	v_lshlrev_b32_e32 v99, 2, v4
	v_xor_b32_e32 v4, 4, v2
	v_cmp_lt_i32_e32 vcc, v4, v3
	s_movk_i32 s36, 0xfc00
	v_lshlrev_b64 v[12:13], 3, v[0:1]
	v_cndmask_b32_e32 v4, v2, v4, vcc
	v_lshlrev_b32_e32 v100, 2, v4
	v_xor_b32_e32 v4, 8, v2
	v_cmp_lt_i32_e32 vcc, v4, v3
	s_mov_b32 s55, 0x17001000
	s_mov_b32 s54, 0x3fb504f3
	v_cndmask_b32_e32 v4, v2, v4, vcc
	v_lshlrev_b32_e32 v101, 2, v4
	v_xor_b32_e32 v4, 16, v2
	v_cmp_lt_i32_e32 vcc, v4, v3
	v_mov_b32_e32 v104, 0x3727c5ac
	s_mov_b32 s56, 0xf800000
	v_cndmask_b32_e32 v4, v2, v4, vcc
	v_lshlrev_b32_e32 v102, 2, v4
	v_xor_b32_e32 v4, 32, v2
	v_cmp_lt_i32_e32 vcc, v4, v3
	v_mov_b32_e32 v105, 0x260
	s_movk_i32 s57, 0x7fff
	v_cndmask_b32_e32 v2, v2, v4, vcc
	v_lshlrev_b32_e32 v103, 2, v2
	v_lshlrev_b64 v[2:3], 4, v[0:1]
	v_lshl_add_u64 v[4:5], s[26:27], 0, v[2:3]
	v_lshl_add_u64 v[2:3], s[28:29], 0, v[2:3]
	v_lshl_add_u64 v[8:9], v[4:5], 0, s[0:1]
	v_lshl_add_u64 v[10:11], v[2:3], 0, s[0:1]
	s_lshl_b64 s[0:1], s[30:31], 9
	s_add_u32 s44, s40, s0
	s_addc_u32 s45, s41, s1
	s_ashr_i32 s37, s36, 31
	s_lshl_b64 s[46:47], s[36:37], 9
	s_lshl_b64 s[0:1], s[30:31], 11
	s_add_u32 s48, s40, s0
	s_addc_u32 s49, s41, s1
	s_lshl_b64 s[52:53], s[36:37], 11
	s_movk_i32 s31, 0xf000
	s_mov_b32 s37, 0x17000000
	s_movk_i32 s30, 0x7ffc
	s_mov_b32 s36, 1

.LBB0_863:
	s_or_b64 exec, exec, s[0:1]
	s_waitcnt lgkmcnt(0)
	v_mov_b32_e32 v0, v180
	s_and_b64 vcc, exec, s[4:5]
	s_barrier
	s_cbranch_vccnz .LBB0_866
	v_mbcnt_hi_u32_b32 v2, -1, v183
	v_and_b32_e32 v3, 64, v2
	v_add_u32_e32 v3, 64, v3
	v_xor_b32_e32 v4, 1, v2
	v_cmp_lt_i32_e32 vcc, v4, v3
	v_ashrrev_i32_e32 v1, 31, v0
	s_bfe_u32 s30, s33, 0x30003
	s_lshl_b32 s30, s30, 12
	s_lshr_b32 s36, s33, 6
	s_lshl_b32 s36, s36, 5
	s_add_i32 s30, s30, s36
	s_and_b32 s36, s33, 7
	s_lshl_b32 s36, s36, 2
	s_add_i32 s30, s30, s36
	s_addk_i32 s30, 0xc00
	v_cndmask_b32_e32 v4, v2, v4, vcc
	v_lshlrev_b32_e32 v84, 2, v4
	v_xor_b32_e32 v4, 2, v2
	v_cmp_lt_i32_e32 vcc, v4, v3
	s_mov_b64 s[0:1], 0x2000
	s_ashr_i32 s31, s30, 31
	v_cndmask_b32_e32 v4, v2, v4, vcc
	v_lshlrev_b32_e32 v85, 2, v4
	v_xor_b32_e32 v4, 4, v2
	v_cmp_lt_i32_e32 vcc, v4, v3
	s_movk_i32 s36, 0xfc00
	v_lshlrev_b64 v[12:13], 3, v[0:1]
	v_cndmask_b32_e32 v4, v2, v4, vcc
	v_lshlrev_b32_e32 v86, 2, v4
	v_xor_b32_e32 v4, 8, v2
	v_cmp_lt_i32_e32 vcc, v4, v3
	s_mov_b32 s55, 0x17001000
	s_mov_b32 s54, 0x3fb504f3
	v_cndmask_b32_e32 v4, v2, v4, vcc
	v_lshlrev_b32_e32 v87, 2, v4
	v_xor_b32_e32 v4, 16, v2
	v_cmp_lt_i32_e32 vcc, v4, v3
	v_mov_b32_e32 v90, 0x3727c5ac
	s_mov_b32 s56, 0xf800000
	v_cndmask_b32_e32 v4, v2, v4, vcc
	v_lshlrev_b32_e32 v88, 2, v4
	v_xor_b32_e32 v4, 32, v2
	v_cmp_lt_i32_e32 vcc, v4, v3
	v_mov_b32_e32 v91, 0x260
	s_movk_i32 s57, 0x7fff
	v_cndmask_b32_e32 v2, v2, v4, vcc
	v_lshlrev_b32_e32 v89, 2, v2
	v_lshlrev_b64 v[2:3], 4, v[0:1]
	v_lshl_add_u64 v[4:5], s[26:27], 0, v[2:3]
	v_lshl_add_u64 v[2:3], s[28:29], 0, v[2:3]
	v_lshl_add_u64 v[8:9], v[4:5], 0, s[0:1]
	v_lshl_add_u64 v[10:11], v[2:3], 0, s[0:1]
	s_lshl_b64 s[0:1], s[30:31], 9
	s_add_u32 s44, s40, s0
	s_addc_u32 s45, s41, s1
	s_ashr_i32 s37, s36, 31
	s_lshl_b64 s[46:47], s[36:37], 9
	s_lshl_b64 s[0:1], s[30:31], 11
	s_add_u32 s48, s40, s0
	s_addc_u32 s49, s41, s1
	s_lshl_b64 s[52:53], s[36:37], 11
	s_movk_i32 s31, 0xf000
	s_mov_b32 s37, 0x17000000
	s_movk_i32 s30, 0x7ffc
	s_mov_b32 s36, 1

.LBB0_1090:
	s_or_b64 exec, exec, s[0:1]
	s_waitcnt lgkmcnt(0)
	v_mov_b32_e32 v0, v180
	s_and_b64 vcc, exec, s[4:5]
	s_barrier
	s_cbranch_vccnz .LBB0_1093
	v_mbcnt_hi_u32_b32 v2, -1, v183
	v_and_b32_e32 v3, 64, v2
	v_add_u32_e32 v3, 64, v3
	v_xor_b32_e32 v4, 1, v2
	v_cmp_lt_i32_e32 vcc, v4, v3
	v_ashrrev_i32_e32 v1, 31, v0
	s_bfe_u32 s36, s33, 0x30003
	s_lshl_b32 s36, s36, 12
	s_lshr_b32 s44, s33, 6
	s_lshl_b32 s44, s44, 5
	s_add_i32 s36, s36, s44
	s_and_b32 s44, s33, 7
	s_lshl_b32 s44, s44, 2
	s_add_i32 s36, s36, s44
	s_addk_i32 s36, 0xc00
	v_cndmask_b32_e32 v4, v2, v4, vcc
	v_lshlrev_b32_e32 v84, 2, v4
	v_xor_b32_e32 v4, 2, v2
	v_cmp_lt_i32_e32 vcc, v4, v3
	s_mov_b64 s[0:1], 0x3000
	s_ashr_i32 s37, s36, 31
	v_cndmask_b32_e32 v4, v2, v4, vcc
	v_lshlrev_b32_e32 v85, 2, v4
	v_xor_b32_e32 v4, 4, v2
	v_cmp_lt_i32_e32 vcc, v4, v3
	s_movk_i32 s44, 0xfc00
	v_lshlrev_b64 v[12:13], 3, v[0:1]
	v_cndmask_b32_e32 v4, v2, v4, vcc
	v_lshlrev_b32_e32 v86, 2, v4
	v_xor_b32_e32 v4, 8, v2
	v_cmp_lt_i32_e32 vcc, v4, v3
	s_mov_b32 s57, 0x17001000
	s_mov_b32 s56, 0x3fb504f3
	v_cndmask_b32_e32 v4, v2, v4, vcc
	v_lshlrev_b32_e32 v87, 2, v4
	v_xor_b32_e32 v4, 16, v2
	v_cmp_lt_i32_e32 vcc, v4, v3
	v_mov_b32_e32 v90, 0x3727c5ac
	s_mov_b32 s58, 0xf800000
	v_cndmask_b32_e32 v4, v2, v4, vcc
	v_lshlrev_b32_e32 v88, 2, v4
	v_xor_b32_e32 v4, 32, v2
	v_cmp_lt_i32_e32 vcc, v4, v3
	v_mov_b32_e32 v91, 0x260
	s_movk_i32 s59, 0x7fff
	v_cndmask_b32_e32 v2, v2, v4, vcc
	v_lshlrev_b32_e32 v89, 2, v2
	v_lshlrev_b64 v[2:3], 4, v[0:1]
	v_lshl_add_u64 v[4:5], s[26:27], 0, v[2:3]
	v_lshl_add_u64 v[2:3], s[28:29], 0, v[2:3]
	v_lshl_add_u64 v[8:9], v[4:5], 0, s[0:1]
	v_lshl_add_u64 v[10:11], v[2:3], 0, s[0:1]
	s_lshl_b64 s[0:1], s[36:37], 9
	s_add_u32 s46, s40, s0
	s_addc_u32 s47, s41, s1
	s_ashr_i32 s45, s44, 31
	s_lshl_b64 s[48:49], s[44:45], 9
	s_lshl_b64 s[0:1], s[36:37], 11
	s_add_u32 s52, s40, s0
	s_addc_u32 s53, s41, s1
	s_lshl_b64 s[54:55], s[44:45], 11
	s_movk_i32 s37, 0xf000
	s_mov_b32 s45, 0x17000000
	s_movk_i32 s36, 0x7ffc
	s_mov_b32 s44, 1

.LBB0_1370:
	s_or_b64 exec, exec, s[0:1]
	s_waitcnt lgkmcnt(0)
	v_mov_b32_e32 v0, v180
	s_and_b64 vcc, exec, s[4:5]
	s_barrier
	s_cbranch_vccnz .LBB0_1373
	v_mbcnt_hi_u32_b32 v2, -1, v183
	v_and_b32_e32 v3, 64, v2
	v_add_u32_e32 v3, 64, v3
	v_xor_b32_e32 v4, 1, v2
	v_cmp_lt_i32_e32 vcc, v4, v3
	v_ashrrev_i32_e32 v1, 31, v0
	s_bfe_u32 s30, s33, 0x30003
	s_lshl_b32 s30, s30, 12
	s_lshr_b32 s36, s33, 6
	s_lshl_b32 s36, s36, 5
	s_add_i32 s30, s30, s36
	s_and_b32 s36, s33, 7
	s_lshl_b32 s36, s36, 2
	s_add_i32 s30, s30, s36
	s_addk_i32 s30, 0xc00
	v_cndmask_b32_e32 v4, v2, v4, vcc
	v_lshlrev_b32_e32 v98, 2, v4
	v_xor_b32_e32 v4, 2, v2
	v_cmp_lt_i32_e32 vcc, v4, v3
	s_mov_b64 s[0:1], 0x4000
	s_ashr_i32 s31, s30, 31
	v_cndmask_b32_e32 v4, v2, v4, vcc
	v_lshlrev_b32_e32 v99, 2, v4
	v_xor_b32_e32 v4, 4, v2
	v_cmp_lt_i32_e32 vcc, v4, v3
	s_movk_i32 s36, 0xfc00
	v_lshlrev_b64 v[12:13], 3, v[0:1]
	v_cndmask_b32_e32 v4, v2, v4, vcc
	v_lshlrev_b32_e32 v100, 2, v4
	v_xor_b32_e32 v4, 8, v2
	v_cmp_lt_i32_e32 vcc, v4, v3
	s_mov_b32 s53, 0x17001000
	s_mov_b32 s52, 0x3fb504f3
	v_cndmask_b32_e32 v4, v2, v4, vcc
	v_lshlrev_b32_e32 v101, 2, v4
	v_xor_b32_e32 v4, 16, v2
	v_cmp_lt_i32_e32 vcc, v4, v3
	v_mov_b32_e32 v104, 0x3727c5ac
	s_mov_b32 s54, 0xf800000
	v_cndmask_b32_e32 v4, v2, v4, vcc
	v_lshlrev_b32_e32 v102, 2, v4
	v_xor_b32_e32 v4, 32, v2
	v_cmp_lt_i32_e32 vcc, v4, v3
	v_mov_b32_e32 v105, 0x260
	s_movk_i32 s55, 0x7fff
	v_cndmask_b32_e32 v2, v2, v4, vcc
	v_lshlrev_b32_e32 v103, 2, v2
	v_lshlrev_b64 v[2:3], 4, v[0:1]
	v_lshl_add_u64 v[4:5], s[26:27], 0, v[2:3]
	v_lshl_add_u64 v[2:3], s[28:29], 0, v[2:3]
	v_lshl_add_u64 v[8:9], v[4:5], 0, s[0:1]
	v_lshl_add_u64 v[10:11], v[2:3], 0, s[0:1]
	s_lshl_b64 s[0:1], s[30:31], 9
	s_add_u32 s44, s40, s0
	s_addc_u32 s45, s41, s1
	s_ashr_i32 s37, s36, 31
	s_lshl_b64 s[46:47], s[36:37], 9
	s_lshl_b64 s[0:1], s[30:31], 11
	s_add_u32 s48, s40, s0
	s_addc_u32 s49, s41, s1
	s_lshl_b64 s[50:51], s[36:37], 11
	s_movk_i32 s31, 0xf000
	s_mov_b32 s37, 0x17000000
	s_movk_i32 s30, 0x7ffc
	s_mov_b32 s36, 1

.LBB0_1573:
	s_or_b64 exec, exec, s[0:1]
	s_and_b64 vcc, exec, s[4:5]
	s_waitcnt lgkmcnt(0)
	s_barrier
	s_cbranch_vccnz .LBB0_1576
	v_mbcnt_hi_u32_b32 v0, -1, v183
	v_and_b32_e32 v1, 64, v0
	v_add_u32_e32 v1, 64, v1
	v_xor_b32_e32 v2, 1, v0
	v_cmp_lt_i32_e32 vcc, v2, v1
	v_ashrrev_i32_e32 v181, 31, v180
	s_bfe_u32 s10, s33, 0x30003
	s_lshl_b32 s10, s10, 12
	s_lshr_b32 s12, s33, 6
	s_lshl_b32 s12, s12, 5
	s_add_i32 s10, s10, s12
	s_and_b32 s12, s33, 7
	s_lshl_b32 s12, s12, 2
	s_add_i32 s10, s10, s12
	s_addk_i32 s10, 0xc00
	v_cndmask_b32_e32 v2, v0, v2, vcc
	v_lshlrev_b32_e32 v84, 2, v2
	v_xor_b32_e32 v2, 2, v0
	v_cmp_lt_i32_e32 vcc, v2, v1
	s_mov_b64 s[0:1], 0x5000
	s_ashr_i32 s11, s10, 31
	v_cndmask_b32_e32 v2, v0, v2, vcc
	v_lshlrev_b32_e32 v85, 2, v2
	v_xor_b32_e32 v2, 4, v0
	v_cmp_lt_i32_e32 vcc, v2, v1
	s_movk_i32 s12, 0xfc00
	v_lshlrev_b64 v[12:13], 3, v[180:181]
	v_cndmask_b32_e32 v2, v0, v2, vcc
	v_lshlrev_b32_e32 v86, 2, v2
	v_xor_b32_e32 v2, 8, v0
	v_cmp_lt_i32_e32 vcc, v2, v1
	s_mov_b32 s25, 0x17001000
	s_mov_b32 s24, 0x3fb504f3
	v_cndmask_b32_e32 v2, v0, v2, vcc
	v_lshlrev_b32_e32 v87, 2, v2
	v_xor_b32_e32 v2, 16, v0
	v_cmp_lt_i32_e32 vcc, v2, v1
	v_mov_b32_e32 v90, 0x3727c5ac
	v_mov_b32_e32 v91, 0x260
	v_cndmask_b32_e32 v2, v0, v2, vcc
	v_lshlrev_b32_e32 v88, 2, v2
	v_xor_b32_e32 v2, 32, v0
	v_cmp_lt_i32_e32 vcc, v2, v1
	s_nop 1
	v_cndmask_b32_e32 v0, v0, v2, vcc
	v_lshlrev_b32_e32 v89, 2, v0
	v_lshlrev_b64 v[0:1], 4, v[180:181]
	v_lshl_add_u64 v[2:3], s[26:27], 0, v[0:1]
	v_lshl_add_u64 v[8:9], v[2:3], 0, s[0:1]
	v_lshl_add_u64 v[2:3], s[28:29], 0, v[0:1]
	v_lshl_add_u64 v[10:11], v[2:3], 0, s[0:1]
	s_lshl_b64 s[0:1], s[10:11], 9
	s_add_u32 s14, s40, s0
	s_addc_u32 s15, s41, s1
	s_ashr_i32 s13, s12, 31
	s_lshl_b64 s[16:17], s[12:13], 9
	s_lshl_b64 s[0:1], s[10:11], 11
	s_add_u32 s18, s40, s0
	s_addc_u32 s19, s41, s1
	s_lshl_b64 s[20:21], s[12:13], 11
	s_lshl_b64 s[0:1], s[10:11], 12
	s_add_u32 s0, s38, s0
	s_addc_u32 s1, s39, s1
	v_lshl_add_u64 v[14:15], s[0:1], 0, v[0:1]
	s_lshl_b64 s[22:23], s[12:13], 12
	s_movk_i32 s11, 0xf000
	s_mov_b32 s13, 0x17000000
	s_mov_b32 s26, 0xf800000
	s_movk_i32 s27, 0x1000
	s_movk_i32 s28, 0x2000
	s_movk_i32 s29, 0x3000
	s_movk_i32 s10, 0x7ffc
	s_mov_b32 s12, 1
